# chain items remapped so the 4 dv-slices of one (b,h,dir) share an XCD L2; on top of blocked W/H layouts and flat->global
# speedup vs baseline: 1.0670x; 1.0080x over previous
.LBB0_155:
	s_and_b64 vcc, exec, s[40:41]
	s_cbranch_vccz .LBB0_174
	s_cmp_gt_i32 s21, 1
	s_mov_b64 s[22:23], -1
	s_cbranch_scc0 .LBB0_172
	s_mov_b32 s25, s13
	s_mov_b32 s35, s16
	s_cmpk_gt_i32 s20, 0xff
	s_cbranch_scc1 .LBB0_171
	v_lshlrev_b32_e32 v112, 4, v134
	v_mov_b32_e32 v113, v1
	s_waitcnt vmcnt(0)
	v_lshl_add_u64 v[2:3], s[94:95], 0, v[112:113]
	s_mov_b64 s[6:7], 0x4800000
	v_lshl_add_u64 v[114:115], v[2:3], 0, s[6:7]
	s_mov_b64 s[6:7], 0xb400000
	v_lshl_add_u64 v[116:117], v[2:3], 0, s[6:7]
	s_mov_b64 s[6:7], 0xd800000
	v_lshl_add_u64 v[118:119], v[2:3], 0, s[6:7]
	v_lshrrev_b32_e32 v0, 3, v134
	v_lshlrev_b32_e32 v2, 3, v134
	v_mul_lo_u32 v0, v0, s96
	v_and_b32_e32 v2, 56, v2
	v_or_b32_e32 v0, v0, v2
	v_lshlrev_b32_e32 v120, 1, v0
	v_add_u32_e32 v0, 0x100, v134
	v_lshrrev_b32_e32 v3, 3, v0
	v_ashrrev_i32_e32 v0, 4, v0
	v_lshlrev_b32_e32 v9, 8, v0
	v_xor_b32_e32 v0, v0, v134
	v_lshlrev_b32_e32 v0, 4, v0
	v_and_b32_e32 v10, 0xf0, v0
	v_add_u32_e32 v0, 0x200, v134
	v_mul_lo_u32 v3, v3, s96
	v_ashrrev_i32_e32 v0, 4, v0
	v_or_b32_e32 v2, v3, v2
	v_lshlrev_b32_e32 v11, 8, v0
	v_xor_b32_e32 v0, v0, v134
	v_lshlrev_b32_e32 v122, 1, v2
	v_lshlrev_b32_e32 v2, 2, v134
	v_lshlrev_b32_e32 v0, 4, v0
	v_ashrrev_i32_e32 v3, 31, v2
	v_and_b32_e32 v12, 0xf0, v0
	v_add_u32_e32 v0, 0x300, v134
	v_and_b32_e32 v110, 15, v134
	v_lshl_add_u64 v[2:3], v[2:3], 2, s[94:95]
	s_mov_b64 s[6:7], 0xfd20000
	v_ashrrev_i32_e32 v0, 4, v0
	v_bfe_u32 v5, v134, 1, 3
	v_lshrrev_b32_e32 v6, 4, v134
	v_bfe_u32 v7, v134, 4, 2
	v_ashrrev_i32_e32 v8, 6, v134
	v_lshl_add_u64 v[124:125], v[2:3], 0, s[6:7]
	v_ashrrev_i32_e32 v2, 4, v134
	v_lshlrev_b32_e32 v13, 8, v0
	v_xor_b32_e32 v0, v0, v134
	v_lshlrev_b32_e32 v111, 7, v110
	v_lshlrev_b32_e32 v3, 8, v2
	v_xor_b32_e32 v2, v2, v134
	v_lshlrev_b32_e32 v0, 4, v0
	v_lshl_or_b32 v113, v8, 11, v111
	v_lshlrev_b32_e32 v126, 4, v8
	v_bitop3_b32 v8, v6, v5, 3 bitop3:0x6c
	v_bitop3_b32 v5, v7, v5, 4 bitop3:0x36
	v_bfe_u32 v6, v6, 1, 1
	v_lshrrev_b32_e32 v4, 1, v134
	v_lshlrev_b32_e32 v2, 4, v2
	v_and_b32_e32 v14, 0xf0, v0
	s_movk_i32 s6, 0x70
	v_lshlrev_b32_e32 v0, 2, v7
	v_lshlrev_b32_e32 v135, 4, v7
	v_lshlrev_b32_e32 v136, 4, v8
	v_lshlrev_b32_e32 v137, 4, v5
	v_add_u32_e32 v5, v111, v111
	v_bitop3_b32 v7, v6, v134, 15 bitop3:0x78
	v_bitop3_b32 v8, v6, v110, 2 bitop3:0x36
	v_bitop3_b32 v17, v6, v110, 4 bitop3:0x36
	v_bitop3_b32 v18, v6, v110, 6 bitop3:0x36
	v_bitop3_b32 v19, v6, v110, 8 bitop3:0x36
	v_bitop3_b32 v20, v6, v110, 10 bitop3:0x36
	v_bitop3_b32 v21, v6, v110, 12 bitop3:0x36
	v_bitop3_b32 v6, v6, v110, 14 bitop3:0x36
	s_add_u32 s4, s94, 0x6c00000
	v_and_b32_e32 v2, 0xf0, v2
	v_and_b32_e32 v15, 0xffffff80, v112
	v_bitop3_b32 v16, v112, s6, v134 bitop3:0x48
	v_and_b32_e32 v4, 8, v4
	v_lshl_add_u32 v7, v7, 4, v5
	v_lshl_add_u32 v8, v8, 4, v5
	v_lshl_add_u32 v17, v17, 4, v5
	v_lshl_add_u32 v18, v18, 4, v5
	v_lshl_add_u32 v19, v19, 4, v5
	v_lshl_add_u32 v20, v20, 4, v5
	v_lshl_add_u32 v21, v21, 4, v5
	v_lshl_add_u32 v5, v6, 4, v5
	s_addc_u32 s5, s95, 0
	v_mov_b32_e32 v121, v1
	v_mov_b32_e32 v123, v1
	v_cmp_gt_i32_e64 s[38:39], 32, v134
	v_ashrrev_i32_e32 v127, 31, v126
	v_lshlrev_b32_e32 v128, 1, v0
	v_add_u32_e32 v138, v3, v2
	v_add_u32_e32 v139, v9, v10
	v_add_u32_e32 v140, v11, v12
	v_add_u32_e32 v141, v13, v14
	v_add_u32_e32 v142, v15, v16
	v_add_u32_e32 v143, v7, v4
	v_add_u32_e32 v144, v8, v4
	v_add_u32_e32 v145, v17, v4
	v_add_u32_e32 v146, v18, v4
	v_add_u32_e32 v147, v19, v4
	v_add_u32_e32 v148, v20, v4
	v_add_u32_e32 v149, v21, v4
	v_add_u32_e32 v150, v5, v4
	s_and_b32 s6, s20, 7
	s_lshl_b32 s6, s6, 5
	s_lshr_b32 s7, s20, 3
	s_or_b32 s6, s6, s7
	s_branch .LBB0_160
